# scoring loop: next K-tile address math and loads issued in the MFMA shadow, guards exit the loop directly, single vmcnt(8) per tile
# speedup vs baseline: 1.0013x; 1.0013x over previous
.LBB0_412:
	s_or_b64 exec, exec, s[0:1]
	s_lshl_b32 s0, s36, 2
	s_sub_i32 s38, 0x200c, s0
	s_sub_i32 s80, 0x210c, s0
	s_cmpk_gt_u32 s80, 0xff
	s_cselect_b64 s[0:1], -1, 0
	s_lshr_b32 s81, s80, 8
	v_mov_b32_e32 v172, v184
	s_cmpk_lt_u32 s80, 0x100
	s_cbranch_scc1 .LBB0_439
	v_readlane_b32 s36, v250, 46
	s_ashr_i32 s39, s38, 31
	v_ashrrev_i32_e32 v0, 5, v172
	v_lshlrev_b32_e32 v168, 3, v172
	v_readlane_b32 s37, v250, 47
	s_lshl_b64 s[48:49], s[38:39], 14
	v_ashrrev_i32_e32 v1, 31, v0
	v_lshl_add_u64 v[96:97], v[168:169], 1, s[36:37]
	s_add_u32 s36, s50, s48
	s_addc_u32 s37, s51, s49
	v_lshlrev_b64 v[2:3], 1, v[0:1]
	v_lshl_add_u64 v[4:5], s[36:37], 0, v[2:3]
	s_or_b32 s36, s38, 1
	s_ashr_i32 s37, s36, 31
	s_lshl_b64 s[44:45], s[36:37], 14
	s_add_u32 s36, s50, s44
	s_addc_u32 s37, s51, s45
	v_lshl_add_u64 v[6:7], s[36:37], 0, v[2:3]
	s_or_b32 s36, s38, 2
	s_ashr_i32 s37, s36, 31
	s_lshl_b64 s[46:47], s[36:37], 14
	s_add_u32 s36, s50, s46
	s_addc_u32 s37, s51, s47
	v_lshl_add_u64 v[8:9], s[36:37], 0, v[2:3]
	s_or_b32 s36, s38, 3
	s_ashr_i32 s37, s36, 31
	s_lshl_b64 s[42:43], s[36:37], 14
	s_movk_i32 s15, 0x1000
	s_add_u32 s36, s50, s42
	v_add_co_u32_e32 v6, vcc, s15, v6
	s_addc_u32 s37, s51, s43
	s_nop 0
	v_addc_co_u32_e32 v7, vcc, 0, v7, vcc
	v_lshl_add_u64 v[10:11], s[36:37], 0, v[2:3]
	v_add_co_u32_e32 v10, vcc, s15, v10
	v_readlane_b32 s39, v250, 54
	s_nop 0
	v_addc_co_u32_e32 v11, vcc, 0, v11, vcc
	s_add_u32 s36, s39, s48
	v_readlane_b32 s58, v250, 55
	s_addc_u32 s37, s58, s49
	v_add_co_u32_e32 v4, vcc, s15, v4
	v_lshl_add_u64 v[12:13], s[36:37], 0, v[2:3]
	s_nop 0
	v_addc_co_u32_e32 v5, vcc, 0, v5, vcc
	s_add_u32 s36, s39, s44
	v_add_co_u32_e32 v12, vcc, s15, v12
	s_addc_u32 s37, s58, s45
	s_nop 0
	v_addc_co_u32_e32 v13, vcc, 0, v13, vcc
	v_lshl_add_u64 v[14:15], s[36:37], 0, v[2:3]
	v_add_co_u32_e32 v14, vcc, s15, v14
	s_add_u32 s36, s39, s46
	s_nop 0
	v_addc_co_u32_e32 v15, vcc, 0, v15, vcc
	s_addc_u32 s37, s58, s47
	v_add_co_u32_e32 v8, vcc, s15, v8
	v_lshl_add_u64 v[16:17], s[36:37], 0, v[2:3]
	s_nop 0
	v_addc_co_u32_e32 v9, vcc, 0, v9, vcc
	s_add_u32 s36, s39, s42
	v_add_co_u32_e32 v16, vcc, s15, v16
	s_addc_u32 s37, s58, s43
	v_readlane_b32 s39, v250, 56
	v_addc_co_u32_e32 v17, vcc, 0, v17, vcc
	v_lshl_add_u64 v[18:19], s[36:37], 0, v[2:3]
	s_add_u32 s36, s39, s48
	v_readlane_b32 s58, v250, 57
	v_add_co_u32_e32 v18, vcc, s15, v18
	s_addc_u32 s37, s58, s49
	s_nop 0
	v_addc_co_u32_e32 v19, vcc, 0, v19, vcc
	v_mov_b32_e32 v241, 0x1680
	s_add_u32 s100, s50, s48
	s_addc_u32 s101, s51, s49
	global_load_dwordx4 v[224:227], v241, s[100:101]
	s_add_u32 s100, s50, s44
	s_addc_u32 s101, s51, s45
	global_load_dwordx4 v[228:231], v241, s[100:101]
	s_add_u32 s100, s50, s46
	s_addc_u32 s101, s51, s47
	global_load_dwordx4 v[232:235], v241, s[100:101]
	s_add_u32 s100, s50, s42
	s_addc_u32 s101, s51, s43
	global_load_dwordx4 v[236:239], v241, s[100:101]
	v_lshl_add_u64 v[4:5], s[36:37], 0, v[2:3]
	s_add_u32 s36, s39, s44
	s_addc_u32 s37, s58, s45
	v_lshl_add_u64 v[6:7], s[36:37], 0, v[2:3]
	s_add_u32 s36, s39, s46
	s_addc_u32 s37, s58, s47
	v_lshl_add_u64 v[8:9], s[36:37], 0, v[2:3]
	s_add_u32 s36, s39, s42
	v_add_co_u32_e32 v6, vcc, s15, v6
	s_addc_u32 s37, s58, s43
	s_nop 0
	v_addc_co_u32_e32 v7, vcc, 0, v7, vcc
	v_lshl_add_u64 v[10:11], s[36:37], 0, v[2:3]
	v_add_co_u32_e32 v10, vcc, s15, v10
	v_readlane_b32 s39, v250, 58
	s_nop 0
	v_addc_co_u32_e32 v11, vcc, 0, v11, vcc
	s_add_u32 s36, s39, s48
	v_readlane_b32 s48, v250, 59
	s_addc_u32 s37, s48, s49
	v_add_co_u32_e32 v4, vcc, s15, v4
	v_lshl_add_u64 v[12:13], s[36:37], 0, v[2:3]
	s_nop 0
	v_addc_co_u32_e32 v5, vcc, 0, v5, vcc
	s_add_u32 s36, s39, s44
	v_add_co_u32_e32 v12, vcc, s15, v12
	s_addc_u32 s37, s48, s45
	s_nop 0
	v_addc_co_u32_e32 v13, vcc, 0, v13, vcc
	v_lshl_add_u64 v[14:15], s[36:37], 0, v[2:3]
	v_add_co_u32_e32 v14, vcc, s15, v14
	s_add_u32 s36, s39, s46
	s_nop 0
	v_addc_co_u32_e32 v15, vcc, 0, v15, vcc
	s_addc_u32 s37, s48, s47
	v_add_co_u32_e32 v8, vcc, s15, v8
	v_lshl_add_u64 v[16:17], s[36:37], 0, v[2:3]
	s_nop 0
	v_addc_co_u32_e32 v9, vcc, 0, v9, vcc
	s_add_u32 s36, s39, s42
	v_add_co_u32_e32 v16, vcc, s15, v16
	s_addc_u32 s37, s48, s43
	s_nop 0
	v_addc_co_u32_e32 v17, vcc, 0, v17, vcc
	v_lshl_add_u64 v[2:3], s[36:37], 0, v[2:3]
	v_add_co_u32_e32 v2, vcc, s15, v2
	v_and_or_b32 v168, v172, 3, s38
	s_nop 0
	v_addc_co_u32_e32 v3, vcc, 0, v3, vcc
	v_lshlrev_b64 v[2:3], 14, v[168:169]
	v_lshlrev_b32_e32 v4, 5, v172
	s_add_i32 s39, s81, 0x7ffffff
	v_lshl_add_u64 v[2:3], s[50:51], 0, v[2:3]
	v_and_b32_e32 v168, 0x380, v4
	v_lshlrev_b32_e32 v4, 3, v0
	v_lshl_add_u64 v[2:3], v[2:3], 0, v[168:169]
	v_ashrrev_i32_e32 v5, 31, v4
	s_lshl_b32 s44, s39, 5
	v_lshl_add_u64 v[2:3], v[4:5], 1, v[2:3]
	s_mov_b64 s[36:37], 0x1200
	s_cmpk_lt_u32 s80, 0x300
	v_lshl_add_u64 v[4:5], v[2:3], 0, s[36:37]
	s_cselect_b32 s36, s44, 64
	s_add_i32 s36, s36, s76
	s_or_b32 s42, s36, 3
	v_add_co_u32_e32 v2, vcc, s15, v2
	s_ashr_i32 s43, s42, 31
	s_nop 0
	v_addc_co_u32_e32 v3, vcc, 0, v3, vcc
	s_lshl_b64 s[42:43], s[42:43], 10
	global_load_dwordx4 v[16:19], v[4:5], off offset:64
	global_load_dwordx4 v[20:23], v[4:5], off offset:32
	global_load_dwordx4 v[24:27], v[4:5], off offset:96
	global_load_dwordx4 v[28:31], v[2:3], off offset:512
	v_lshl_add_u64 v[2:3], v[96:97], 0, s[42:43]
	s_or_b32 s42, s36, 2
	s_ashr_i32 s43, s42, 31
	s_lshl_b64 s[42:43], s[42:43], 10
	v_lshl_add_u64 v[4:5], v[96:97], 0, s[42:43]
	s_or_b32 s42, s36, 1
	s_ashr_i32 s43, s42, 31
	s_ashr_i32 s37, s36, 31
	s_lshl_b64 s[42:43], s[42:43], 10
	s_lshl_b64 s[36:37], s[36:37], 10
	s_cmpk_lt_u32 s80, 0x200
	global_load_dwordx4 v[48:51], v[2:3], off
	global_load_dwordx4 v[52:55], v[4:5], off
	v_lshl_add_u64 v[4:5], v[96:97], 0, s[36:37]
	s_cselect_b32 s36, s44, 32
	s_add_i32 s36, s36, s76
	v_lshl_add_u64 v[2:3], v[96:97], 0, s[42:43]
	s_or_b32 s42, s36, 3
	s_ashr_i32 s43, s42, 31
	s_lshl_b64 s[42:43], s[42:43], 10
	global_load_dwordx4 v[56:59], v[2:3], off
	global_load_dwordx4 v[60:63], v[4:5], off
	v_lshl_add_u64 v[2:3], v[96:97], 0, s[42:43]
	s_or_b32 s42, s36, 2
	s_ashr_i32 s43, s42, 31
	s_lshl_b64 s[42:43], s[42:43], 10
	v_lshl_add_u64 v[4:5], v[96:97], 0, s[42:43]
	s_or_b32 s42, s36, 1
	s_ashr_i32 s37, s36, 31
	s_ashr_i32 s43, s42, 31
	s_lshl_b64 s[36:37], s[36:37], 10
	global_load_dwordx4 v[64:67], v[2:3], off
	global_load_dwordx4 v[68:71], v[4:5], off
	s_lshl_b64 s[42:43], s[42:43], 10
	v_lshl_add_u64 v[4:5], v[96:97], 0, s[36:37]
	v_readlane_b32 s36, v251, 50
	v_lshl_add_u64 v[2:3], v[96:97], 0, s[42:43]
	v_readlane_b32 s37, v251, 51
	global_load_dwordx4 v[72:75], v[2:3], off
	global_load_dwordx4 v[76:79], v[4:5], off
	v_lshl_add_u64 v[2:3], v[96:97], 0, s[36:37]
	v_lshl_add_u64 v[4:5], v[96:97], 0, s[6:7]
	global_load_dwordx4 v[40:43], v[2:3], off
	global_load_dwordx4 v[44:47], v[4:5], off
	v_lshl_add_u64 v[2:3], v[96:97], 0, s[10:11]
	v_lshl_add_u64 v[4:5], v[96:97], 0, s[12:13]
	global_load_dwordx4 v[32:35], v[2:3], off
	global_load_dwordx4 v[36:39], v[4:5], off
	v_lshrrev_b32_e32 v240, 5, v172
	v_sub_u32_e32 v240, 1, v240
	v_lshlrev_b32_e32 v240, 4, v240
	s_waitcnt vmcnt(16)
	v_lshlrev_b32_e32 v242, v240, v224
	v_and_b32_e32 v98, 0xffff0000, v242
	v_lshlrev_b32_e32 v242, v240, v228
	v_and_b32_e32 v106, 0xffff0000, v242
	v_lshlrev_b32_e32 v242, v240, v232
	v_and_b32_e32 v100, 0xffff0000, v242
	v_lshlrev_b32_e32 v242, v240, v236
	v_and_b32_e32 v107, 0xffff0000, v242
	v_lshlrev_b32_e32 v242, v240, v225
	v_and_b32_e32 v99, 0xffff0000, v242
	v_lshlrev_b32_e32 v242, v240, v229
	v_and_b32_e32 v108, 0xffff0000, v242
	v_lshlrev_b32_e32 v242, v240, v233
	v_and_b32_e32 v101, 0xffff0000, v242
	v_lshlrev_b32_e32 v242, v240, v237
	v_and_b32_e32 v109, 0xffff0000, v242
	v_lshlrev_b32_e32 v242, v240, v226
	v_and_b32_e32 v102, 0xffff0000, v242
	v_lshlrev_b32_e32 v242, v240, v230
	v_and_b32_e32 v110, 0xffff0000, v242
	v_lshlrev_b32_e32 v242, v240, v234
	v_and_b32_e32 v104, 0xffff0000, v242
	v_lshlrev_b32_e32 v242, v240, v238
	v_and_b32_e32 v111, 0xffff0000, v242
	v_lshlrev_b32_e32 v242, v240, v227
	v_and_b32_e32 v103, 0xffff0000, v242
	v_lshlrev_b32_e32 v242, v240, v231
	v_and_b32_e32 v112, 0xffff0000, v242
	v_lshlrev_b32_e32 v242, v240, v235
	v_and_b32_e32 v105, 0xffff0000, v242
	v_lshlrev_b32_e32 v242, v240, v239
	v_and_b32_e32 v113, 0xffff0000, v242
	v_lshlrev_b32_e32 v1, 1, v0
	s_mov_b32 s36, 0x10800
	v_and_b32_e32 v2, 31, v172
	v_mul_lo_u32 v3, v0, s36
	v_lshl_add_u32 v115, v0, 13, s17
	v_or_b32_e32 v0, 1, v1
	v_add_u32_e32 v116, s38, v0
	v_lshl_add_u32 v117, v0, 12, s17
	v_lshl_or_b32 v0, v2, 2, v3
	v_add_u32_e32 v114, s38, v1
	v_add_u32_e32 v118, s4, v2
	v_add_u32_e32 v119, s14, v0
	s_waitcnt vmcnt(0)
	s_mov_b32 s46, 6
	s_branch .LBB0_416

.LBB0_416:
	s_add_i32 s47, s46, -6
	s_cmp_lt_u32 s47, s81
	s_cbranch_scc0 .LBB0_439
	s_waitcnt vmcnt(8)
	v_mfma_f32_32x32x16_bf16 v[0:15], v[28:31], v[36:39], 0
	v_cmp_le_i32_e32 vcc, v118, v114
	v_mfma_f32_32x32x16_bf16 v[0:15], v[20:23], v[32:35], v[0:15]
	v_mfma_f32_32x32x16_bf16 v[0:15], v[16:19], v[44:47], v[0:15]
	v_mfma_f32_32x32x16_bf16 v[0:15], v[24:27], v[40:43], v[0:15]
	s_add_i32 s47, s46, -6
	s_add_i32 s44, s46, -3
	s_cmp_lt_u32 s44, s81
	s_cselect_b64 s[42:43], -1, 0
	s_and_b64 s[36:37], s[42:43], exec
	s_cselect_b32 s36, s44, s39
	s_lshl_b32 s36, s36, 5
	s_add_i32 s36, s36, s76
	s_ashr_i32 s37, s36, 31
	s_lshl_b64 s[44:45], s[36:37], 10
	v_lshl_add_u64 v[244:245], v[96:97], 0, s[44:45]
	s_or_b32 s44, s36, 1
	s_ashr_i32 s45, s44, 31
	s_lshl_b64 s[44:45], s[44:45], 10
	v_lshl_add_u64 v[246:247], v[96:97], 0, s[44:45]
	s_or_b32 s44, s36, 2
	s_ashr_i32 s45, s44, 31
	s_or_b32 s36, s36, 3
	s_lshl_b64 s[44:45], s[44:45], 10
	s_ashr_i32 s37, s36, 31
	global_load_dwordx4 v[84:87], v[244:245], off
	global_load_dwordx4 v[80:83], v[246:247], off
	v_lshl_add_u64 v[244:245], v[96:97], 0, s[44:45]
	s_lshl_b64 s[36:37], s[36:37], 10
	v_lshl_add_u64 v[246:247], v[96:97], 0, s[36:37]
	global_load_dwordx4 v[88:91], v[244:245], off
	global_load_dwordx4 v[92:95], v[246:247], off
	s_nop 3
	v_max_i32_e32 v33, 0, v4
	v_max_i32_e32 v32, 0, v0
	v_max_i32_e32 v0, 0, v5
	v_max_i32_e32 v5, 0, v6
	v_max_i32_e32 v34, 0, v8
	v_max_i32_e32 v36, 0, v1
	v_max_i32_e32 v4, 0, v2
	v_max_i32_e32 v8, 0, v10
	v_max_i32_e32 v1, 0, v7
	v_max_i32_e32 v7, 0, v11
	v_max_i32_e32 v11, 0, v15
	v_mul_f32_e32 v2, v99, v33
	v_mul_f32_e32 v10, v101, v5
	v_max_i32_e32 v35, 0, v12
	v_max_i32_e32 v37, 0, v9
	v_max_i32_e32 v9, 0, v14
	v_max_i32_e32 v14, 0, v3
	v_pk_fma_f32 v[2:3], v[98:99], v[32:33], v[2:3] op_sel_hi:[1,1,0]
	v_pk_fma_f32 v[4:5], v[100:101], v[4:5], v[10:11] op_sel_hi:[1,1,0]
	v_max_i32_e32 v13, 0, v13
	v_mul_f32_e32 v6, v103, v35
	v_mul_f32_e32 v12, v105, v9
	v_pk_fma_f32 v[2:3], v[102:103], v[34:35], v[2:3]
	v_pk_fma_f32 v[4:5], v[104:105], v[8:9], v[4:5]
	v_pk_add_f32 v[2:3], v[2:3], v[6:7] op_sel_hi:[1,0]
	v_pk_add_f32 v[4:5], v[4:5], v[12:13] op_sel_hi:[1,0]
	v_mul_f32_e32 v0, v108, v0
	s_nop 0
	v_permlane32_swap_b32_e32 v2, v4
	v_add_f32_e32 v2, v2, v4
	v_mul_f32_e32 v1, v109, v1
	v_add_f32_e32 v2, 0, v2
	v_fmac_f32_e32 v0, v106, v36
	v_fmac_f32_e32 v1, v107, v14
	v_ashrrev_i32_e32 v3, 31, v2
	v_fmac_f32_e32 v0, v110, v37
	v_fmac_f32_e32 v1, v111, v7
	v_bitop3_b32 v2, v3, v2, s33 bitop3:0x36
	v_fmac_f32_e32 v0, v112, v13
	v_fmac_f32_e32 v1, v113, v11
	v_cndmask_b32_e32 v2, 0, v2, vcc
	s_nop 0
	v_permlane32_swap_b32_e32 v0, v1
	v_cmp_ne_u32_e32 vcc, 0, v2
	ds_write_b32 v119, v2
	s_and_saveexec_b64 s[44:45], vcc
	s_cbranch_execz .LBB0_419
	v_lshrrev_b32_e32 v3, 20, v2
	v_lshrrev_b32_e32 v2, 17, v2
	v_and_b32_e32 v3, 0xffc, v3
	v_and_b32_e32 v2, 16, v2
	v_add_u32_e32 v3, v115, v3
	v_lshlrev_b32_e64 v2, v2, 1
	ds_add_u32 v3, v2

.LBB0_421:
	s_or_b64 exec, exec, s[44:45]
	s_add_i32 s48, s46, -5
	s_cmp_ge_u32 s48, s81
	s_cbranch_scc1 .LBB0_439
	s_waitcnt vmcnt(8)
	v_mfma_f32_32x32x16_bf16 v[0:15], v[28:31], v[76:79], 0
	v_mfma_f32_32x32x16_bf16 v[0:15], v[20:23], v[72:75], v[0:15]
	v_mfma_f32_32x32x16_bf16 v[0:15], v[16:19], v[68:71], v[0:15]
	v_mfma_f32_32x32x16_bf16 v[0:15], v[24:27], v[64:67], v[0:15]
	v_add_u32_e32 v64, 0x100, v118
	v_cmp_le_i32_e32 vcc, v64, v114
	s_add_i32 s48, s46, -5
	s_add_i32 s47, s46, -2
	s_cmp_lt_u32 s47, s81
	s_cselect_b32 s36, s47, s39
	s_lshl_b32 s36, s36, 5
	s_add_i32 s36, s36, s76
	s_ashr_i32 s37, s36, 31
	s_lshl_b64 s[44:45], s[36:37], 10
	v_lshl_add_u64 v[244:245], v[96:97], 0, s[44:45]
	s_or_b32 s44, s36, 1
	s_ashr_i32 s45, s44, 31
	s_lshl_b64 s[44:45], s[44:45], 10
	v_lshl_add_u64 v[246:247], v[96:97], 0, s[44:45]
	s_or_b32 s44, s36, 2
	s_ashr_i32 s45, s44, 31
	s_or_b32 s36, s36, 3
	s_lshl_b64 s[44:45], s[44:45], 10
	s_ashr_i32 s37, s36, 31
	global_load_dwordx4 v[36:39], v[244:245], off
	global_load_dwordx4 v[32:35], v[246:247], off
	v_lshl_add_u64 v[244:245], v[96:97], 0, s[44:45]
	s_lshl_b64 s[36:37], s[36:37], 10
	v_lshl_add_u64 v[246:247], v[96:97], 0, s[36:37]
	global_load_dwordx4 v[44:47], v[244:245], off
	global_load_dwordx4 v[40:43], v[246:247], off
	s_nop 3
	v_max_i32_e32 v67, 0, v4
	v_max_i32_e32 v66, 0, v0
	v_mul_f32_e32 v0, v99, v67
	v_pk_fma_f32 v[66:67], v[98:99], v[66:67], v[0:1] op_sel_hi:[1,1,0]
	v_max_i32_e32 v69, 0, v12
	v_max_i32_e32 v68, 0, v8
	v_pk_fma_f32 v[66:67], v[102:103], v[68:69], v[66:67]
	v_mul_f32_e32 v0, v103, v69
	v_pk_add_f32 v[66:67], v[66:67], v[0:1] op_sel_hi:[1,0]
	v_max_i32_e32 v0, 0, v5
	v_max_i32_e32 v1, 0, v1
	v_mul_f32_e32 v0, v108, v0
	v_max_i32_e32 v5, 0, v6
	v_fmac_f32_e32 v0, v106, v1
	v_max_i32_e32 v1, 0, v9
	v_max_i32_e32 v4, 0, v2
	v_mul_f32_e32 v2, v101, v5
	v_fmac_f32_e32 v0, v110, v1
	v_max_i32_e32 v1, 0, v13
	v_pk_fma_f32 v[4:5], v[100:101], v[4:5], v[2:3] op_sel_hi:[1,1,0]
	v_max_i32_e32 v9, 0, v14
	v_max_i32_e32 v8, 0, v10
	v_fmac_f32_e32 v0, v112, v1
	v_pk_fma_f32 v[4:5], v[104:105], v[8:9], v[4:5]
	v_mul_f32_e32 v2, v105, v9
	v_max_i32_e32 v1, 0, v7
	v_pk_add_f32 v[4:5], v[4:5], v[2:3] op_sel_hi:[1,0]
	v_max_i32_e32 v2, 0, v3
	v_mul_f32_e32 v1, v109, v1
	v_fmac_f32_e32 v1, v107, v2
	v_max_i32_e32 v2, 0, v11
	v_fmac_f32_e32 v1, v111, v2
	v_max_i32_e32 v2, 0, v15
	v_permlane32_swap_b32_e32 v66, v4
	v_fmac_f32_e32 v1, v113, v2
	v_add_f32_e32 v2, v66, v4
	v_add_f32_e32 v2, 0, v2
	v_ashrrev_i32_e32 v3, 31, v2
	v_bitop3_b32 v2, v3, v2, s33 bitop3:0x36
	v_cndmask_b32_e32 v2, 0, v2, vcc
	v_permlane32_swap_b32_e32 v0, v1
	v_cmp_ne_u32_e32 vcc, 0, v2
	ds_write_b32 v119, v2 offset:1024
	s_and_saveexec_b64 s[44:45], vcc
	s_cbranch_execz .LBB0_425
	v_lshrrev_b32_e32 v3, 20, v2
	v_lshrrev_b32_e32 v2, 17, v2
	v_and_b32_e32 v3, 0xffc, v3
	v_and_b32_e32 v2, 16, v2
	v_add_u32_e32 v3, v115, v3
	v_lshlrev_b32_e64 v2, v2, 1
	ds_add_u32 v3, v2

.LBB0_427:
	s_or_b64 exec, exec, s[44:45]
	s_add_i32 s48, s46, -4
	s_cmp_ge_u32 s48, s81
	s_cbranch_scc1 .LBB0_439
	s_waitcnt vmcnt(8)
	v_mfma_f32_32x32x16_bf16 v[0:15], v[28:31], v[60:63], 0
	v_mfma_f32_32x32x16_bf16 v[0:15], v[20:23], v[56:59], v[0:15]
	v_mfma_f32_32x32x16_bf16 v[0:15], v[16:19], v[52:55], v[0:15]
	v_mfma_f32_32x32x16_bf16 v[0:15], v[24:27], v[48:51], v[0:15]
	v_add_u32_e32 v48, 0x200, v118
	v_cmp_le_i32_e32 vcc, v48, v114
	s_add_i32 s48, s46, -4
	s_add_i32 s36, s46, -1
	s_cmp_lt_u32 s36, s81
	s_cselect_b32 s36, s36, s39
	s_lshl_b32 s36, s36, 5
	s_add_i32 s36, s36, s76
	s_ashr_i32 s37, s36, 31
	s_lshl_b64 s[44:45], s[36:37], 10
	v_lshl_add_u64 v[244:245], v[96:97], 0, s[44:45]
	s_or_b32 s44, s36, 1
	s_ashr_i32 s45, s44, 31
	s_lshl_b64 s[44:45], s[44:45], 10
	v_lshl_add_u64 v[246:247], v[96:97], 0, s[44:45]
	s_or_b32 s44, s36, 2
	s_ashr_i32 s45, s44, 31
	s_or_b32 s36, s36, 3
	s_lshl_b64 s[44:45], s[44:45], 10
	s_ashr_i32 s37, s36, 31
	global_load_dwordx4 v[76:79], v[244:245], off
	global_load_dwordx4 v[72:75], v[246:247], off
	v_lshl_add_u64 v[244:245], v[96:97], 0, s[44:45]
	s_lshl_b64 s[36:37], s[36:37], 10
	v_lshl_add_u64 v[246:247], v[96:97], 0, s[36:37]
	global_load_dwordx4 v[68:71], v[244:245], off
	global_load_dwordx4 v[64:67], v[246:247], off
	s_nop 3
	v_max_i32_e32 v51, 0, v4
	v_max_i32_e32 v50, 0, v0
	v_mul_f32_e32 v0, v99, v51
	v_pk_fma_f32 v[50:51], v[98:99], v[50:51], v[0:1] op_sel_hi:[1,1,0]
	v_max_i32_e32 v53, 0, v12
	v_max_i32_e32 v52, 0, v8
	v_pk_fma_f32 v[50:51], v[102:103], v[52:53], v[50:51]
	v_mul_f32_e32 v0, v103, v53
	v_pk_add_f32 v[50:51], v[50:51], v[0:1] op_sel_hi:[1,0]
	v_max_i32_e32 v0, 0, v5
	v_max_i32_e32 v1, 0, v1
	v_mul_f32_e32 v0, v108, v0
	v_max_i32_e32 v5, 0, v6
	v_fmac_f32_e32 v0, v106, v1
	v_max_i32_e32 v1, 0, v9
	v_max_i32_e32 v4, 0, v2
	v_mul_f32_e32 v2, v101, v5
	v_fmac_f32_e32 v0, v110, v1
	v_max_i32_e32 v1, 0, v13
	v_pk_fma_f32 v[4:5], v[100:101], v[4:5], v[2:3] op_sel_hi:[1,1,0]
	v_max_i32_e32 v9, 0, v14
	v_max_i32_e32 v8, 0, v10
	v_fmac_f32_e32 v0, v112, v1
	v_pk_fma_f32 v[4:5], v[104:105], v[8:9], v[4:5]
	v_mul_f32_e32 v2, v105, v9
	v_max_i32_e32 v1, 0, v7
	v_pk_add_f32 v[4:5], v[4:5], v[2:3] op_sel_hi:[1,0]
	v_max_i32_e32 v2, 0, v3
	v_mul_f32_e32 v1, v109, v1
	v_fmac_f32_e32 v1, v107, v2
	v_max_i32_e32 v2, 0, v11
	v_fmac_f32_e32 v1, v111, v2
	v_max_i32_e32 v2, 0, v15
	v_permlane32_swap_b32_e32 v50, v4
	v_fmac_f32_e32 v1, v113, v2
	v_add_f32_e32 v2, v50, v4
	v_add_f32_e32 v2, 0, v2
	v_ashrrev_i32_e32 v3, 31, v2
	v_bitop3_b32 v2, v3, v2, s33 bitop3:0x36
	v_cndmask_b32_e32 v2, 0, v2, vcc
	v_permlane32_swap_b32_e32 v0, v1
	v_cmp_ne_u32_e32 vcc, 0, v2
	ds_write_b32 v119, v2 offset:2048
	s_and_saveexec_b64 s[44:45], vcc
	s_cbranch_execz .LBB0_431
	v_lshrrev_b32_e32 v3, 20, v2
	v_lshrrev_b32_e32 v2, 17, v2
	v_and_b32_e32 v3, 0xffc, v3
	v_and_b32_e32 v2, 16, v2
	v_add_u32_e32 v3, v115, v3
	v_lshlrev_b32_e64 v2, v2, 1
	ds_add_u32 v3, v2

.LBB0_433:
	s_or_b64 exec, exec, s[44:45]
	s_add_i32 s48, s46, -3
	s_cmp_ge_u32 s48, s81
	s_cbranch_scc1 .LBB0_439
	s_waitcnt vmcnt(8)
	v_mfma_f32_32x32x16_bf16 v[0:15], v[28:31], v[84:87], 0
	v_mfma_f32_32x32x16_bf16 v[0:15], v[20:23], v[80:83], v[0:15]
	v_add_u32_e32 v80, 0x300, v118
	v_cmp_le_i32_e32 vcc, v80, v114
	v_mfma_f32_32x32x16_bf16 v[0:15], v[16:19], v[88:91], v[0:15]
	v_mfma_f32_32x32x16_bf16 v[0:15], v[24:27], v[92:95], v[0:15]
	s_cmp_lt_u32 s46, s81
	s_cselect_b32 s36, s46, s39
	s_lshl_b32 s36, s36, 5
	s_add_i32 s36, s36, s76
	s_ashr_i32 s37, s36, 31
	s_lshl_b64 s[44:45], s[36:37], 10
	v_lshl_add_u64 v[244:245], v[96:97], 0, s[44:45]
	s_or_b32 s44, s36, 1
	s_ashr_i32 s45, s44, 31
	s_lshl_b64 s[44:45], s[44:45], 10
	v_lshl_add_u64 v[246:247], v[96:97], 0, s[44:45]
	s_or_b32 s44, s36, 2
	s_ashr_i32 s45, s44, 31
	s_or_b32 s36, s36, 3
	s_lshl_b64 s[44:45], s[44:45], 10
	s_ashr_i32 s37, s36, 31
	global_load_dwordx4 v[60:63], v[244:245], off
	global_load_dwordx4 v[56:59], v[246:247], off
	v_lshl_add_u64 v[244:245], v[96:97], 0, s[44:45]
	s_lshl_b64 s[36:37], s[36:37], 10
	v_lshl_add_u64 v[246:247], v[96:97], 0, s[36:37]
	global_load_dwordx4 v[52:55], v[244:245], off
	global_load_dwordx4 v[48:51], v[246:247], off
	s_nop 3
	v_max_i32_e32 v83, 0, v4
	v_max_i32_e32 v82, 0, v0
	v_mul_f32_e32 v0, v99, v83
	v_pk_fma_f32 v[82:83], v[98:99], v[82:83], v[0:1] op_sel_hi:[1,1,0]
	v_max_i32_e32 v85, 0, v12
	v_max_i32_e32 v84, 0, v8
	v_pk_fma_f32 v[82:83], v[102:103], v[84:85], v[82:83]
	v_mul_f32_e32 v0, v103, v85
	v_pk_add_f32 v[82:83], v[82:83], v[0:1] op_sel_hi:[1,0]
	v_max_i32_e32 v0, 0, v5
	v_max_i32_e32 v1, 0, v1
	v_mul_f32_e32 v0, v108, v0
	v_max_i32_e32 v5, 0, v6
	v_fmac_f32_e32 v0, v106, v1
	v_max_i32_e32 v1, 0, v9
	v_max_i32_e32 v4, 0, v2
	v_mul_f32_e32 v2, v101, v5
	v_fmac_f32_e32 v0, v110, v1
	v_max_i32_e32 v1, 0, v13
	v_pk_fma_f32 v[4:5], v[100:101], v[4:5], v[2:3] op_sel_hi:[1,1,0]
	v_max_i32_e32 v9, 0, v14
	v_max_i32_e32 v8, 0, v10
	v_fmac_f32_e32 v0, v112, v1
	v_pk_fma_f32 v[4:5], v[104:105], v[8:9], v[4:5]
	v_mul_f32_e32 v2, v105, v9
	v_max_i32_e32 v1, 0, v7
	v_pk_add_f32 v[4:5], v[4:5], v[2:3] op_sel_hi:[1,0]
	v_max_i32_e32 v2, 0, v3
	v_mul_f32_e32 v1, v109, v1
	v_fmac_f32_e32 v1, v107, v2
	v_max_i32_e32 v2, 0, v11
	v_fmac_f32_e32 v1, v111, v2
	v_max_i32_e32 v2, 0, v15
	v_permlane32_swap_b32_e32 v82, v4
	v_fmac_f32_e32 v1, v113, v2
	v_add_f32_e32 v2, v82, v4
	v_add_f32_e32 v2, 0, v2
	v_ashrrev_i32_e32 v3, 31, v2
	v_bitop3_b32 v2, v3, v2, s33 bitop3:0x36
	v_cndmask_b32_e32 v2, 0, v2, vcc
	v_permlane32_swap_b32_e32 v0, v1
	v_cmp_ne_u32_e32 vcc, 0, v2
	ds_write_b32 v119, v2 offset:3072
	s_and_saveexec_b64 s[42:43], vcc
	s_cbranch_execz .LBB0_437
	v_lshrrev_b32_e32 v3, 20, v2
	v_lshrrev_b32_e32 v2, 17, v2
	v_and_b32_e32 v3, 0xffc, v3
	v_and_b32_e32 v2, 16, v2
	v_add_u32_e32 v3, v115, v3
	v_lshlrev_b32_e64 v2, v2, 1
	ds_add_u32 v3, v2
